# software prefetch: next-row touch load (one dword per 128-byte line, oldest in the vmcnt queue) in both large norm row loops
# baseline (speedup 1.0000x reference)
; #define GAS __attribute__((address_space(1)))
; DI void phase_norm(const Ctx& C, const float* xlat, const float* xctx, bf16_t* H, const float* gn, const float* modl, int sh_off, int sc_off, int nrows, const float* part, int nsplit, float* xs_out) {
;     ...
;     for (int row = gw; row < nrows; row += NGW) {
;         const int b = row < NLAT ? (row >> 11) : 4;
;         const float* mb = modl + (size_t)b * MODW;
;         const GAS f32x4* xr = (const GAS f32x4*)(row < NLAT ? xlat + (size_t)row * DM : xctx + (size_t)(row - NLAT) * DM) + lane;
;         f32x4 v[8]; float s = 0.f;
; #pragma unroll
;         for (int j = 0; j < 8; ++j) v[j] = __builtin_nontemporal_load(xr + 64 * j);
.LBB0_692:
	s_add_i32 s98, s4, s6
	s_cmpk_gt_i32 s98, 0x23ff
	s_cbranch_scc1 .Lnpf_2
	s_add_i32 s99, s98, 0xffffe000
	s_cmpk_lt_i32 s98, 0x2000
	s_cselect_b32 s98, s98, s99
	s_cselect_b32 s94, s15, s17
	s_cselect_b32 s93, s14, s16
	s_mov_b32 s99, 0
	s_lshl_b64 s[98:99], s[98:99], 13
	s_add_u32 s98, s93, s98
	s_addc_u32 s99, s94, s99
	v_lshlrev_b32_e32 v70, 7, v206
	v_mov_b32_e32 v71, 0
	v_lshl_add_u64 v[70:71], v[70:71], 0, s[98:99]
	global_load_dword v68, v[70:71], off
